# GEMM prologues: K-tile 1's six LDS-DMA pieces issued straight behind K-tile 0's eight, first wait vmcnt(8) instead of vmcnt(2)+barrier in between
# baseline (speedup 1.0000x reference)
; #define PG8_STAGE(bufoff, gbase, voff) do { _Pragma("unroll") for (int _i = 0; _i < 2; ++_i) \
;         __builtin_amdgcn_global_load_lds((const unsigned*)((const char*)(gbase) + (voff)[_i]), (PG8_LAS unsigned*)(lds + (bufoff) + ldsw + _i * 8192), 16, 0, 0); } while (0)
; #define PG8_WAIT_V(n) asm volatile("s_waitcnt vmcnt(" #n ")" ::: "memory")
; #define PG8_BAR __builtin_amdgcn_s_barrier()
; template <class Epi, class Sched, bool ALIGN_EPI = false, bool SP2 = false>
; __device__ __forceinline__ void gemm_phase(PG8_LAS unsigned char* lds, const Gemm g, const Sched& S, const Epi& E) {
;     ...
;     const char* cA = (const char*)g.A + (size_t)cur.pm * tstep + cur.kh * khb; const char* cB = (const char*)g.Bt + (size_t)cur.pn * tstep + cur.kh * khb;
;     S.a_ready(cur);
;     if constexpr (SP2) {
;         PG8_STAGE(PG8_SB(0, 0), cB, voffB); PG8_STAGE(PG8_SB(0, 1), cB + hstep, voffB); PG8_STAGE(PG8_SA(0, 0), cA, voffA); PG8_STAGE(PG8_SA(0, 1), cA + hstep, voffA);
;         if (wr == 1) PG8_BAR;
;         PG8_WAIT_V(2); PG8_BAR;
;         PG8_STAGE(PG8_SB(1, 0), cB + kstep, voffB); PG8_STAGE(PG8_SA(1, 0), cA + kstep, voffA); PG8_STAGE(PG8_SB(1, 1), cB + hstep + kstep, voffB);
;         PG8_WAIT_V(6); PG8_BAR;
.LBB0_90:
	s_add_u32 s14, s72, 0x4b00000
	s_addc_u32 s15, s73, 0
	s_add_u32 s16, s72, 0x8b00000
	s_addc_u32 s17, s73, 0
	s_add_u32 s18, s72, 0xab00000
	s_addc_u32 s19, s73, 0
	s_add_u32 s22, s72, 0xcb00000
	s_addc_u32 s23, s73, 0
	v_writelane_b32 v254, s22, 13
	s_waitcnt vmcnt(0)
	v_bfe_u32 v16, v13, 4, 2
	v_and_b32_e32 v15, 15, v13
	v_writelane_b32 v254, s23, 14
	s_add_u32 s22, s72, 0xdb00000
	s_addc_u32 s23, s73, 0
	s_add_u32 s24, s72, 0xeb00000
	v_lshlrev_b32_e32 v17, 4, v16
	v_lshlrev_b32_e32 v13, 2, v13
	s_mov_b64 s[26:27], 0x80
	s_sext_i32_i16 s1, s2
	v_writelane_b32 v254, s22, 15
	s_addc_u32 s25, s73, 0
	s_and_b32 s2, s3, 3
	v_lshl_or_b32 v155, s20, 6, v15
	v_lshl_or_b32 v15, v15, 6, v17
	s_lshl_b32 s20, s20, 13
	v_and_b32_e32 v13, 32, v13
	s_add_i32 m0, s93, 0x18000
	v_lshl_add_u64 v[6:7], v[6:7], 0, s[26:27]
	v_writelane_b32 v254, s23, 16
	v_bitop3_b32 v17, v15, s20, v13 bitop3:0xde
	s_lshl_b32 s22, s2, 5
	s_lshl_b32 s20, s2, 12
	global_load_lds_dwordx4 v[6:7], off
	v_lshl_add_u64 v[4:5], v[4:5], 0, s[26:27]
	s_add_i32 m0, s93, 0x1a000
	s_add_i32 s42, s93, 0x8000
	s_add_i32 s43, s93, 0xa000
	v_bitop3_b32 v176, v15, s20, v13 bitop3:0xde
	global_load_lds_dwordx4 v[4:5], off
	v_lshl_add_u64 v[2:3], v[2:3], 0, s[26:27]
	s_mov_b32 m0, s42
	s_add_u32 s20, s82, 0x40080
	global_load_lds_dwordx4 v[2:3], off
	v_lshl_add_u64 v[0:1], v[0:1], 0, s[26:27]
	s_mov_b32 m0, s43
	s_addc_u32 s21, s83, 0
	global_load_lds_dwordx4 v[0:1], off
	s_add_i32 m0, s93, 0x1c000
	v_lshl_add_u64 v[0:1], s[20:21], 0, v[148:149]
	global_load_lds_dwordx4 v[0:1], off
	v_lshl_add_u64 v[0:1], s[20:21], 0, v[144:145]
	s_add_i32 m0, s93, 0x1e000
	s_cmpk_lt_u32 s8, 0x100
	global_load_lds_dwordx4 v[0:1], off
	s_waitcnt vmcnt(8)
	s_barrier
	v_lshlrev_b32_e32 v0, 14, v12
	v_and_b32_e32 v0, 0xffff8000, v0
	v_lshl_add_u32 v0, v11, 11, v0
	v_and_b32_e32 v1, 1, v12
	v_lshl_or_b32 v0, v1, 6, v0
	v_lshl_add_u32 v158, v14, 1, v0
	v_lshlrev_b32_e32 v0, 14, v8
	v_and_b32_e32 v0, 0xffff8000, v0
	s_cselect_b64 s[28:29], -1, 0
	s_lshl_b32 s96, s2, 6
	s_lshl_b32 s2, s3, 17
	v_lshl_add_u32 v0, v9, 11, v0
	v_and_b32_e32 v1, 1, v8
	s_waitcnt vmcnt(6)
	s_and_b32 s2, s2, 0x20000
	v_lshl_or_b32 v0, v1, 6, v0
	v_lshlrev_b32_e32 v154, 3, v16
	v_lshl_or_b32 v152, v16, 15, s2
	v_lshl_add_u32 v160, v10, 1, v0
	s_add_i32 s23, 0, 0x10000
	s_add_i32 s41, 0, 0x14000
	v_mbcnt_lo_u32_b32 v0, -1, 0
	v_writelane_b32 v254, s22, 17
	v_or_b32_e32 v177, s22, v154
	s_ashr_i32 s44, s84, 31
	s_mov_b32 s45, s84
	v_lshl_add_u64 v[156:157], s[6:7], 0, v[152:153]
	v_mov_b32_e32 v159, v153
	v_mov_b32_e32 v161, v153
	v_mov_b64_e32 v[162:163], 0x600
	v_mov_b64_e32 v[164:165], 0x5ff
	v_add_u32_e32 v178, s23, v176
	v_add_u32_e32 v179, s41, v176
	v_add_u32_e32 v181, 0, v17
	s_mov_b64 s[38:39], 0x2c000
	s_mov_b32 s22, 0x2c000
	s_movk_i32 s30, 0x7000
	v_mov_b32_e32 v182, 0x358637bd
	s_mov_b64 s[46:47], 0x800
	v_mov_b32_e32 v183, 0x3e38aa3b
	v_mbcnt_hi_u32_b32 v184, -1, v0
	s_mov_b32 s31, 0
	s_barrier
	s_branch .LBB0_93

; #define PG8_STAGE(bufoff, gbase, voff) do { _Pragma("unroll") for (int _i = 0; _i < 2; ++_i) \
;         __builtin_amdgcn_global_load_lds((const unsigned*)((const char*)(gbase) + (voff)[_i]), (PG8_LAS unsigned*)(lds + (bufoff) + ldsw + _i * 8192), 16, 0, 0); } while (0)
; #define PG8_WAIT_V(n) asm volatile("s_waitcnt vmcnt(" #n ")" ::: "memory")
; #define PG8_BAR __builtin_amdgcn_s_barrier()
; template <class Epi, class Sched, bool ALIGN_EPI = false, bool SP2 = false>
; __device__ __forceinline__ void gemm_phase(PG8_LAS unsigned char* lds, const Gemm g, const Sched& S, const Epi& E) {
;     ...
;     const char* cA = (const char*)g.A + (size_t)cur.pm * tstep + cur.kh * khb; const char* cB = (const char*)g.Bt + (size_t)cur.pn * tstep + cur.kh * khb;
;     S.a_ready(cur);
;     if constexpr (SP2) {
;         PG8_STAGE(PG8_SB(0, 0), cB, voffB); PG8_STAGE(PG8_SB(0, 1), cB + hstep, voffB); PG8_STAGE(PG8_SA(0, 0), cA, voffA); PG8_STAGE(PG8_SA(0, 1), cA + hstep, voffA);
;         if (wr == 1) PG8_BAR;
;         PG8_WAIT_V(2); PG8_BAR;
;         PG8_STAGE(PG8_SB(1, 0), cB + kstep, voffB); PG8_STAGE(PG8_SA(1, 0), cA + kstep, voffA); PG8_STAGE(PG8_SB(1, 1), cB + hstep + kstep, voffB);
;         PG8_WAIT_V(6); PG8_BAR;
.LBB0_140:
	s_lshl_b32 s38, s8, 6
	s_lshl_b32 s14, s8, 13
	s_lshl_b32 s8, s9, 5
	s_and_b32 s15, s8, 0x60
	s_mov_b64 s[8:9], 0x80
	s_add_i32 m0, s13, 0x18000
	v_lshl_add_u64 v[6:7], v[6:7], 0, s[8:9]
	s_lshl_b32 s16, s15, 7
	global_load_lds_dwordx4 v[6:7], off
	v_lshl_add_u64 v[4:5], v[4:5], 0, s[8:9]
	s_add_i32 m0, s13, 0x1a000
	s_add_i32 s39, s13, 0x8000
	s_add_i32 s40, s13, 0xa000
	global_load_lds_dwordx4 v[4:5], off
	v_lshl_add_u64 v[0:1], v[0:1], 0, s[8:9]
	s_mov_b32 m0, s39
	s_add_u32 s10, s24, 0x40080
	global_load_lds_dwordx4 v[0:1], off
	v_lshl_add_u64 v[0:1], v[2:3], 0, s[8:9]
	s_mov_b32 m0, s40
	s_addc_u32 s11, s25, 0
	global_load_lds_dwordx4 v[0:1], off
	s_add_i32 m0, s13, 0x1c000
	v_lshl_add_u64 v[0:1], s[10:11], 0, v[130:131]
	global_load_lds_dwordx4 v[0:1], off
	v_lshl_add_u64 v[0:1], s[10:11], 0, v[134:135]
	s_add_i32 m0, s13, 0x1e000
	v_lshlrev_b32_e32 v3, 2, v8
	global_load_lds_dwordx4 v[0:1], off
	s_waitcnt vmcnt(8)
	s_barrier
	v_lshrrev_b32_e32 v1, 1, v8
	v_and_b32_e32 v1, 24, v1
	v_and_b32_e32 v0, 15, v8
	v_lshlrev_b32_e32 v2, 1, v1
	v_or_b32_e32 v153, s15, v1
	v_lshlrev_b32_e32 v1, 14, v9
	v_lshl_or_b32 v2, v0, 6, v2
	v_and_b32_e32 v3, 32, v3
	v_and_b32_e32 v1, 0xffff8000, v1
	v_bitop3_b32 v5, v2, s14, v3 bitop3:0xde
	v_bitop3_b32 v152, v2, s16, v3 bitop3:0xde
	v_lshl_add_u32 v1, v10, 11, v1
	v_and_b32_e32 v3, 1, v9
	v_lshl_or_b32 v1, v3, 6, v1
	v_lshl_add_u32 v138, v11, 1, v1
	v_lshlrev_b32_e32 v1, 14, v12
	v_and_b32_e32 v1, 0xffff8000, v1
	s_waitcnt vmcnt(6)
	s_cmpk_lt_u32 s3, 0x100
	v_lshlrev_b32_e32 v0, 11, v0
	v_lshl_add_u32 v1, v13, 11, v1
	v_and_b32_e32 v3, 1, v12
	s_cselect_b64 s[10:11], -1, 0
	v_or_b32_e32 v2, 0x8000, v0
	v_or_b32_e32 v4, 0x10000, v0
	v_or_b32_e32 v6, 0x18000, v0
	v_lshl_or_b32 v1, v3, 6, v1
	s_add_i32 s43, 0, 0x14000
	s_sext_i32_i16 s44, s2
	s_ashr_i32 s41, s84, 31
	s_mov_b32 s42, s84
	v_mov_b32_e32 v139, v137
	v_lshl_add_u32 v140, v14, 1, v1
	v_mov_b32_e32 v141, v137
	v_mov_b64_e32 v[142:143], 0x100
	v_mov_b64_e32 v[144:145], 0xff
	v_add_u32_e32 v154, s43, v152
	v_add_u32_e32 v155, 0, v5
	v_lshlrev_b32_e32 v136, 1, v0
	v_lshlrev_b32_e32 v146, 1, v2
	v_lshlrev_b32_e32 v148, 1, v4
	v_lshlrev_b32_e32 v150, 1, v6
	s_barrier
	s_branch .LBB0_143

; #define PG8_STAGE(bufoff, gbase, voff) do { _Pragma("unroll") for (int _i = 0; _i < 2; ++_i) \
;         __builtin_amdgcn_global_load_lds((const unsigned*)((const char*)(gbase) + (voff)[_i]), (PG8_LAS unsigned*)(lds + (bufoff) + ldsw + _i * 8192), 16, 0, 0); } while (0)
; #define PG8_WAIT_V(n) asm volatile("s_waitcnt vmcnt(" #n ")" ::: "memory")
; #define PG8_BAR __builtin_amdgcn_s_barrier()
; template <class Epi, class Sched, bool ALIGN_EPI = false, bool SP2 = false>
; __device__ __forceinline__ void gemm_phase(PG8_LAS unsigned char* lds, const Gemm g, const Sched& S, const Epi& E) {
;     ...
;     const char* cA = (const char*)g.A + (size_t)cur.pm * tstep + cur.kh * khb; const char* cB = (const char*)g.Bt + (size_t)cur.pn * tstep + cur.kh * khb;
;     S.a_ready(cur);
;     if constexpr (SP2) {
;         PG8_STAGE(PG8_SB(0, 0), cB, voffB); PG8_STAGE(PG8_SB(0, 1), cB + hstep, voffB); PG8_STAGE(PG8_SA(0, 0), cA, voffA); PG8_STAGE(PG8_SA(0, 1), cA + hstep, voffA);
;         if (wr == 1) PG8_BAR;
;         PG8_WAIT_V(2); PG8_BAR;
;         PG8_STAGE(PG8_SB(1, 0), cB + kstep, voffB); PG8_STAGE(PG8_SA(1, 0), cA + kstep, voffA); PG8_STAGE(PG8_SB(1, 1), cB + hstep + kstep, voffB);
;         PG8_WAIT_V(6); PG8_BAR;
.LBB0_348:
	s_waitcnt vmcnt(0)
	v_bfe_u32 v16, v8, 4, 2
	v_and_b32_e32 v15, 15, v8
	v_lshlrev_b32_e32 v17, 4, v16
	v_lshlrev_b32_e32 v8, 2, v8
	s_mov_b64 s[10:11], 0x80
	s_and_b32 s1, s2, 3
	v_lshl_or_b32 v155, s3, 6, v15
	v_lshl_or_b32 v15, v15, 6, v17
	s_lshl_b32 s3, s3, 13
	v_and_b32_e32 v8, 32, v8
	s_add_i32 m0, s47, 0x18000
	v_lshl_add_u64 v[6:7], v[6:7], 0, s[10:11]
	v_bitop3_b32 v17, v15, s3, v8 bitop3:0xde
	s_lshl_b32 s79, s1, 5
	s_lshl_b32 s3, s1, 12
	global_load_lds_dwordx4 v[6:7], off
	v_lshl_add_u64 v[4:5], v[4:5], 0, s[10:11]
	s_add_i32 m0, s47, 0x1a000
	s_add_i32 s80, s47, 0x8000
	s_add_i32 s81, s47, 0xa000
	global_load_lds_dwordx4 v[4:5], off
	v_lshl_add_u64 v[2:3], v[2:3], 0, s[10:11]
	s_mov_b32 m0, s80
	s_add_u32 s12, s42, 0x40080
	global_load_lds_dwordx4 v[2:3], off
	v_lshl_add_u64 v[0:1], v[0:1], 0, s[10:11]
	s_mov_b32 m0, s81
	s_addc_u32 s13, s43, 0
	global_load_lds_dwordx4 v[0:1], off
	s_add_i32 m0, s47, 0x1c000
	v_lshl_add_u64 v[0:1], s[12:13], 0, v[146:147]
	global_load_lds_dwordx4 v[0:1], off
	v_lshl_add_u64 v[0:1], s[12:13], 0, v[150:151]
	s_add_i32 m0, s47, 0x1e000
	s_cmpk_lt_u32 s6, 0x100
	global_load_lds_dwordx4 v[0:1], off
	s_waitcnt vmcnt(8)
	s_barrier
	v_lshlrev_b32_e32 v0, 14, v9
	v_and_b32_e32 v0, 0xffff8000, v0
	v_lshl_add_u32 v0, v10, 11, v0
	v_and_b32_e32 v1, 1, v9
	v_lshl_or_b32 v0, v1, 6, v0
	v_lshl_add_u32 v158, v11, 1, v0
	v_lshlrev_b32_e32 v0, 14, v12
	v_and_b32_e32 v0, 0xffff8000, v0
	s_cselect_b64 s[12:13], -1, 0
	s_lshl_b32 s82, s1, 6
	s_lshl_b32 s1, s2, 17
	v_lshl_add_u32 v0, v13, 11, v0
	v_and_b32_e32 v1, 1, v12
	v_bitop3_b32 v176, v15, s3, v8 bitop3:0xde
	s_waitcnt vmcnt(6)
	s_and_b32 s1, s1, 0x20000
	v_readlane_b32 s2, v254, 22
	v_lshl_or_b32 v0, v1, 6, v0
	v_lshlrev_b32_e32 v154, 3, v16
	v_lshl_or_b32 v152, v16, 15, s1
	v_readlane_b32 s3, v254, 23
	v_lshl_add_u32 v160, v14, 1, v0
	s_add_i32 s93, 0, 0x10000
	s_add_i32 s94, 0, 0x14000
	v_mbcnt_lo_u32_b32 v0, -1, 0
	v_or_b32_e32 v177, s79, v154
	s_ashr_i32 s83, s84, 31
	s_mov_b32 s88, s84
	s_ashr_i32 s89, s33, 31
	s_mov_b32 s92, 0x20000
	v_lshl_add_u64 v[156:157], s[2:3], 0, v[152:153]
	v_mov_b32_e32 v159, v153
	v_mov_b32_e32 v161, v153
	v_mov_b64_e32 v[162:163], 0x200
	v_mov_b64_e32 v[164:165], 0x1ff
	v_add_u32_e32 v178, s93, v176
	v_add_u32_e32 v179, s94, v176
	v_add_u32_e32 v181, 0, v17
	s_mov_b64 s[14:15], 0x20000
	s_mov_b64 s[16:17], 0x24000
	s_mov_b32 s95, 0x24000
	s_mov_b64 s[18:19], 0x28000
	s_mov_b32 s96, 0x28000
	s_mov_b64 s[20:21], 0x2c000
	s_mov_b32 s6, 0x2c000
	s_movk_i32 s7, 0x7000
	s_mov_b64 s[26:27], 0x58000
	s_mov_b32 s22, 0x58000
	v_mov_b32_e32 v182, 0x358637bd
	s_mov_b64 s[28:29], 0x800
	v_mov_b32_e32 v183, 0x3e38aa3b
	v_mbcnt_hi_u32_b32 v184, -1, v0
	s_mov_b32 s97, 0
	s_barrier
	s_branch .LBB0_351

; #define PG8_STAGE(bufoff, gbase, voff) do { _Pragma("unroll") for (int _i = 0; _i < 2; ++_i) \
;         __builtin_amdgcn_global_load_lds((const unsigned*)((const char*)(gbase) + (voff)[_i]), (PG8_LAS unsigned*)(lds + (bufoff) + ldsw + _i * 8192), 16, 0, 0); } while (0)
; #define PG8_WAIT_V(n) asm volatile("s_waitcnt vmcnt(" #n ")" ::: "memory")
; #define PG8_BAR __builtin_amdgcn_s_barrier()
; template <class Epi, class Sched, bool ALIGN_EPI = false, bool SP2 = false>
; __device__ __forceinline__ void gemm_phase(PG8_LAS unsigned char* lds, const Gemm g, const Sched& S, const Epi& E) {
;     ...
;     const char* cA = (const char*)g.A + (size_t)cur.pm * tstep + cur.kh * khb; const char* cB = (const char*)g.Bt + (size_t)cur.pn * tstep + cur.kh * khb;
;     S.a_ready(cur);
;     if constexpr (SP2) {
;         PG8_STAGE(PG8_SB(0, 0), cB, voffB); PG8_STAGE(PG8_SB(0, 1), cB + hstep, voffB); PG8_STAGE(PG8_SA(0, 0), cA, voffA); PG8_STAGE(PG8_SA(0, 1), cA + hstep, voffA);
;         if (wr == 1) PG8_BAR;
;         PG8_WAIT_V(2); PG8_BAR;
;         PG8_STAGE(PG8_SB(1, 0), cB + kstep, voffB); PG8_STAGE(PG8_SA(1, 0), cA + kstep, voffA); PG8_STAGE(PG8_SB(1, 1), cB + hstep + kstep, voffB);
;         PG8_WAIT_V(6); PG8_BAR;
.LBB0_672:
	s_mov_b64 s[14:15], 0x80
	s_and_b32 s3, s0, 3
	s_add_i32 m0, s47, 0x18000
	v_lshl_add_u64 v[6:7], v[6:7], 0, s[14:15]
	s_lshl_b32 s5, s1, 13
	s_lshl_b32 s61, s3, 5
	s_lshl_b32 s8, s3, 12
	global_load_lds_dwordx4 v[6:7], off
	v_lshl_add_u64 v[4:5], v[4:5], 0, s[14:15]
	s_add_i32 m0, s47, 0x1a000
	s_add_i32 s66, s47, 0x8000
	s_add_i32 s67, s47, 0xa000
	global_load_lds_dwordx4 v[4:5], off
	v_lshl_add_u64 v[2:3], v[2:3], 0, s[14:15]
	s_mov_b32 m0, s66
	s_add_u32 s18, s12, 0x40080
	global_load_lds_dwordx4 v[2:3], off
	v_lshl_add_u64 v[0:1], v[0:1], 0, s[14:15]
	s_mov_b32 m0, s67
	s_addc_u32 s19, s13, 0
	global_load_lds_dwordx4 v[0:1], off
	s_add_i32 m0, s47, 0x1c000
	v_lshl_add_u64 v[0:1], s[18:19], 0, v[146:147]
	global_load_lds_dwordx4 v[0:1], off
	v_lshl_add_u64 v[0:1], s[18:19], 0, v[150:151]
	s_add_i32 m0, s47, 0x1e000
	s_cmpk_lt_u32 s6, 0x100
	global_load_lds_dwordx4 v[0:1], off
	s_waitcnt vmcnt(8)
	s_barrier
	v_bfe_u32 v1, v8, 4, 2
	v_and_b32_e32 v0, 15, v8
	v_lshlrev_b32_e32 v2, 4, v1
	v_lshl_or_b32 v155, s1, 6, v0
	v_lshl_or_b32 v0, v0, 6, v2
	v_lshlrev_b32_e32 v2, 2, v8
	v_and_b32_e32 v2, 32, v2
	v_bitop3_b32 v3, v0, s5, v2 bitop3:0xde
	v_bitop3_b32 v172, v0, s8, v2 bitop3:0xde
	s_cselect_b64 s[18:19], -1, 0
	s_lshl_b32 s0, s0, 17
	v_lshlrev_b32_e32 v0, 14, v9
	s_and_b32 s0, s0, 0x20000
	v_and_b32_e32 v0, 0xffff8000, v0
	v_lshlrev_b32_e32 v154, 3, v1
	v_lshl_or_b32 v152, v1, 15, s0
	v_lshl_add_u32 v0, v10, 11, v0
	v_and_b32_e32 v1, 1, v9
	v_lshl_or_b32 v0, v1, 6, v0
	v_lshl_add_u32 v158, v11, 1, v0
	v_lshlrev_b32_e32 v0, 14, v12
	v_and_b32_e32 v0, 0xffff8000, v0
	v_lshl_add_u32 v0, v13, 11, v0
	v_and_b32_e32 v1, 1, v12
	s_waitcnt vmcnt(6)
	v_readlane_b32 s0, v254, 22
	v_lshl_or_b32 v0, v1, 6, v0
	v_readlane_b32 s1, v254, 23
	v_lshl_add_u32 v160, v14, 1, v0
	s_add_i32 s76, 0, 0x10000
	s_add_i32 s77, 0, 0x14000
	v_mbcnt_lo_u32_b32 v0, -1, 0
	v_or_b32_e32 v173, s61, v154
	s_lshl_b32 s68, s3, 6
	s_mov_b32 s69, 0x20000
	v_lshl_add_u64 v[156:157], s[0:1], 0, v[152:153]
	v_mov_b32_e32 v159, v153
	v_mov_b32_e32 v161, v153
	v_add_u32_e32 v174, s76, v172
	v_add_u32_e32 v175, s77, v172
	v_add_u32_e32 v176, 0, v3
	s_mov_b64 s[20:21], 0x20000
	s_mov_b64 s[22:23], 0x24000
	s_mov_b32 s78, 0x24000
	s_mov_b64 s[24:25], 0x28000
	s_mov_b32 s79, 0x28000
	s_mov_b64 s[26:27], 0x2c000
	s_mov_b32 s80, 0x2c000
	s_movk_i32 s81, 0x7000
	s_mov_b32 s82, 0x40000
	s_mov_b64 s[28:29], 0x48000
	s_mov_b32 s83, 0x48000
	s_mov_b64 s[30:31], 0x50000
	s_mov_b32 s88, 0x50000
	s_mov_b64 s[34:35], 0x58000
	s_mov_b32 s89, 0x58000
	v_mov_b32_e32 v177, 0x358637bd
	s_mov_b64 s[36:37], 0x800
	v_mov_b32_e32 v178, 0x3e38aa3b
	v_mbcnt_hi_u32_b32 v179, -1, v0
	s_mov_b32 s92, 0
	s_barrier
	s_branch .LBB0_675

; #define PG8_STAGE(bufoff, gbase, voff) do { _Pragma("unroll") for (int _i = 0; _i < 2; ++_i) \
;         __builtin_amdgcn_global_load_lds((const unsigned*)((const char*)(gbase) + (voff)[_i]), (PG8_LAS unsigned*)(lds + (bufoff) + ldsw + _i * 8192), 16, 0, 0); } while (0)
; #define PG8_WAIT_V(n) asm volatile("s_waitcnt vmcnt(" #n ")" ::: "memory")
; #define PG8_BAR __builtin_amdgcn_s_barrier()
; template <class Epi, class Sched, bool ALIGN_EPI = false, bool SP2 = false>
; __device__ __forceinline__ void gemm_phase(PG8_LAS unsigned char* lds, const Gemm g, const Sched& S, const Epi& E) {
;     ...
;     const char* cA = (const char*)g.A + (size_t)cur.pm * tstep + cur.kh * khb; const char* cB = (const char*)g.Bt + (size_t)cur.pn * tstep + cur.kh * khb;
;     S.a_ready(cur);
;     if constexpr (SP2) {
;         PG8_STAGE(PG8_SB(0, 0), cB, voffB); PG8_STAGE(PG8_SB(0, 1), cB + hstep, voffB); PG8_STAGE(PG8_SA(0, 0), cA, voffA); PG8_STAGE(PG8_SA(0, 1), cA + hstep, voffA);
;         if (wr == 1) PG8_BAR;
;         PG8_WAIT_V(2); PG8_BAR;
;         PG8_STAGE(PG8_SB(1, 0), cB + kstep, voffB); PG8_STAGE(PG8_SA(1, 0), cA + kstep, voffA); PG8_STAGE(PG8_SB(1, 1), cB + hstep + kstep, voffB);
;         PG8_WAIT_V(6); PG8_BAR;
.LBB0_785:
	s_add_u32 s8, s72, 0xdb00000
	s_addc_u32 s9, s73, 0
	s_add_u32 s10, s72, 0xeb00000
	v_lshrrev_b32_e32 v16, 1, v9
	s_addc_u32 s11, s73, 0
	v_and_b32_e32 v136, 24, v16
	s_add_u32 s12, s72, 0x2b00000
	v_and_b32_e32 v15, 15, v9
	v_lshlrev_b32_e32 v16, 1, v136
	v_lshlrev_b32_e32 v9, 2, v9
	s_sext_i32_i8 s77, s2
	s_addc_u32 s13, s73, 0
	v_lshl_or_b32 v139, s3, 6, v15
	v_lshl_or_b32 v15, v15, 6, v16
	s_lshl_b32 s2, s3, 13
	v_and_b32_e32 v9, 32, v9
	v_bitop3_b32 v16, v15, s2, v9 bitop3:0xde
	s_lshl_b32 s2, s14, 5
	s_mov_b64 s[14:15], 0x80
	s_and_b32 s20, s2, 0x60
	s_add_i32 m0, s61, 0x18000
	v_lshl_add_u64 v[6:7], v[6:7], 0, s[14:15]
	s_lshl_b32 s2, s20, 7
	global_load_lds_dwordx4 v[6:7], off
	v_lshl_add_u64 v[4:5], v[4:5], 0, s[14:15]
	s_add_i32 m0, s61, 0x1a000
	s_add_i32 s65, s61, 0x8000
	s_add_i32 s66, s61, 0xa000
	v_bitop3_b32 v186, v15, s2, v9 bitop3:0xde
	global_load_lds_dwordx4 v[4:5], off
	v_lshl_add_u64 v[0:1], v[0:1], 0, s[14:15]
	s_mov_b32 m0, s65
	s_add_u32 s2, s54, 0x80080
	global_load_lds_dwordx4 v[0:1], off
	v_lshl_add_u64 v[0:1], v[2:3], 0, s[14:15]
	s_mov_b32 m0, s66
	s_addc_u32 s3, s55, 0
	global_load_lds_dwordx4 v[0:1], off
	s_add_i32 m0, s61, 0x1c000
	v_lshl_add_u64 v[0:1], s[2:3], 0, v[130:131]
	global_load_lds_dwordx4 v[0:1], off
	v_lshl_add_u64 v[0:1], s[2:3], 0, v[134:135]
	s_add_i32 m0, s61, 0x1e000
	s_cmpk_lt_u32 s4, 0x100
	global_load_lds_dwordx4 v[0:1], off
	s_waitcnt vmcnt(8)
	s_barrier
	v_lshlrev_b32_e32 v0, 15, v8
	v_and_b32_e32 v0, 0xffff0000, v0
	v_lshl_add_u32 v0, v10, 12, v0
	v_and_b32_e32 v1, 1, v8
	v_lshl_or_b32 v0, v1, 6, v0
	v_lshl_add_u32 v142, v11, 1, v0
	v_lshlrev_b32_e32 v0, 15, v12
	v_and_b32_e32 v0, 0xffff0000, v0
	v_lshl_add_u32 v0, v13, 12, v0
	v_and_b32_e32 v1, 1, v12
	s_waitcnt vmcnt(6)
	s_cselect_b64 s[16:17], -1, 0
	s_add_u32 s2, s10, s20
	v_lshl_or_b32 v0, v1, 6, v0
	v_mov_b32_e32 v2, v137
	v_mov_b32_e32 v3, v137
	s_addc_u32 s3, s11, 0
	v_lshl_add_u32 v144, v14, 1, v0
	v_mov_b32_e32 v0, v137
	v_mov_b32_e32 v1, v137
	v_add_u32_e32 v187, 0, v16
	v_mov_b64_e32 v[6:7], v[2:3]
	v_mov_b64_e32 v[10:11], v[2:3]
	v_mov_b64_e32 v[14:15], v[2:3]
	v_mov_b64_e32 v[18:19], v[2:3]
	v_mov_b64_e32 v[22:23], v[2:3]
	v_mov_b64_e32 v[26:27], v[2:3]
	v_mov_b64_e32 v[30:31], v[2:3]
	v_mov_b64_e32 v[34:35], v[2:3]
	v_mov_b64_e32 v[38:39], v[2:3]
	v_mov_b64_e32 v[42:43], v[2:3]
	v_mov_b64_e32 v[46:47], v[2:3]
	v_mov_b64_e32 v[50:51], v[2:3]
	v_mov_b64_e32 v[54:55], v[2:3]
	v_mov_b64_e32 v[58:59], v[2:3]
	v_mov_b64_e32 v[62:63], v[2:3]
	v_mov_b64_e32 v[66:67], v[2:3]
	v_mov_b64_e32 v[70:71], v[2:3]
	v_mov_b64_e32 v[74:75], v[2:3]
	v_mov_b64_e32 v[78:79], v[2:3]
	v_mov_b64_e32 v[82:83], v[2:3]
	v_mov_b64_e32 v[86:87], v[2:3]
	v_mov_b64_e32 v[90:91], v[2:3]
	v_mov_b64_e32 v[94:95], v[2:3]
	v_mov_b64_e32 v[98:99], v[2:3]
	v_mov_b64_e32 v[102:103], v[2:3]
	v_mov_b64_e32 v[106:107], v[2:3]
	v_mov_b64_e32 v[110:111], v[2:3]
	v_mov_b64_e32 v[114:115], v[2:3]
	v_mov_b64_e32 v[118:119], v[2:3]
	v_mov_b64_e32 v[122:123], v[2:3]
	v_mov_b64_e32 v[126:127], v[2:3]
	v_or_b32_e32 v138, s20, v136
	v_lshl_add_u64 v[140:141], s[2:3], 0, v[136:137]
	v_mov_b32_e32 v143, v137
	v_mov_b32_e32 v145, v137
	v_mov_b64_e32 v[146:147], 0x100
	v_mov_b64_e32 v[148:149], 0xff
	s_add_i32 s67, 0, 0x10000
	s_add_i32 s68, 0, 0x14000
	s_mov_b32 s18, 0x3b808081
	s_lshl_b32 s4, s20, 1
	v_lshlrev_b32_e32 v136, 1, v136
	s_mov_b64 s[20:21], 0x20000
	s_mov_b64 s[22:23], 0x20080
	s_mov_b64 s[24:25], 0x24000
	s_mov_b64 s[26:27], 0x24080
	s_mov_b64 s[28:29], 0x28000
	s_mov_b64 s[30:31], 0x28080
	s_mov_b64 s[34:35], 0x2c000
	s_mov_b64 s[36:37], 0x2c080
	v_mov_b64_e32 v[4:5], v[0:1]
	v_mov_b64_e32 v[8:9], v[0:1]
	v_mov_b64_e32 v[12:13], v[0:1]
	v_mov_b64_e32 v[16:17], v[0:1]
	v_mov_b64_e32 v[20:21], v[0:1]
	v_mov_b64_e32 v[24:25], v[0:1]
	v_mov_b64_e32 v[28:29], v[0:1]
	v_mov_b64_e32 v[32:33], v[0:1]
	v_mov_b64_e32 v[36:37], v[0:1]
	v_mov_b64_e32 v[40:41], v[0:1]
	v_mov_b64_e32 v[44:45], v[0:1]
	v_mov_b64_e32 v[48:49], v[0:1]
	v_mov_b64_e32 v[52:53], v[0:1]
	v_mov_b64_e32 v[56:57], v[0:1]
	v_mov_b64_e32 v[60:61], v[0:1]
	v_mov_b64_e32 v[64:65], v[0:1]
	v_mov_b64_e32 v[68:69], v[0:1]
	v_mov_b64_e32 v[72:73], v[0:1]
	v_mov_b64_e32 v[76:77], v[0:1]
	v_mov_b64_e32 v[80:81], v[0:1]
	v_mov_b64_e32 v[84:85], v[0:1]
	v_mov_b64_e32 v[88:89], v[0:1]
	v_mov_b64_e32 v[92:93], v[0:1]
	v_mov_b64_e32 v[96:97], v[0:1]
	v_mov_b64_e32 v[100:101], v[0:1]
	v_mov_b64_e32 v[104:105], v[0:1]
	v_mov_b64_e32 v[108:109], v[0:1]
	v_mov_b64_e32 v[112:113], v[0:1]
	v_mov_b64_e32 v[116:117], v[0:1]
	v_mov_b64_e32 v[120:121], v[0:1]
	v_mov_b64_e32 v[124:125], v[0:1]
	s_mov_b32 s49, s5
	s_mov_b32 s69, s5
	s_barrier
	s_branch .LBB0_788

; #define PG8_STAGE(bufoff, gbase, voff) do { _Pragma("unroll") for (int _i = 0; _i < 2; ++_i) \
;         __builtin_amdgcn_global_load_lds((const unsigned*)((const char*)(gbase) + (voff)[_i]), (PG8_LAS unsigned*)(lds + (bufoff) + ldsw + _i * 8192), 16, 0, 0); } while (0)
; #define PG8_WAIT_V(n) asm volatile("s_waitcnt vmcnt(" #n ")" ::: "memory")
; #define PG8_BAR __builtin_amdgcn_s_barrier()
; template <class Epi, class Sched, bool ALIGN_EPI = false, bool SP2 = false>
; __device__ __forceinline__ void gemm_phase(PG8_LAS unsigned char* lds, const Gemm g, const Sched& S, const Epi& E) {
;     ...
;     const char* cA = (const char*)g.A + (size_t)cur.pm * tstep + cur.kh * khb; const char* cB = (const char*)g.Bt + (size_t)cur.pn * tstep + cur.kh * khb;
;     S.a_ready(cur);
;     if constexpr (SP2) {
;         PG8_STAGE(PG8_SB(0, 0), cB, voffB); PG8_STAGE(PG8_SB(0, 1), cB + hstep, voffB); PG8_STAGE(PG8_SA(0, 0), cA, voffA); PG8_STAGE(PG8_SA(0, 1), cA + hstep, voffA);
;         if (wr == 1) PG8_BAR;
;         PG8_WAIT_V(2); PG8_BAR;
;         PG8_STAGE(PG8_SB(1, 0), cB + kstep, voffB); PG8_STAGE(PG8_SA(1, 0), cA + kstep, voffA); PG8_STAGE(PG8_SB(1, 1), cB + hstep + kstep, voffB);
;         PG8_WAIT_V(6); PG8_BAR;
.LBB0_872:
	s_add_u32 s10, s72, 0xdb00000
	s_addc_u32 s11, s73, 0
	s_add_u32 s12, s72, 0xab00000
	s_addc_u32 s13, s73, 0
	s_add_u32 s14, s72, 0x100000
	s_mov_b64 s[16:17], 0x80
	s_addc_u32 s15, s73, 0
	s_and_b32 s47, s2, 3
	s_add_i32 m0, s43, 0x18000
	v_lshl_add_u64 v[6:7], v[6:7], 0, s[16:17]
	s_lshl_b32 s2, s3, 13
	s_lshl_b32 s19, s47, 12
	global_load_lds_dwordx4 v[6:7], off
	v_lshl_add_u64 v[4:5], v[4:5], 0, s[16:17]
	s_add_i32 m0, s43, 0x1a000
	s_add_i32 s48, s43, 0x8000
	s_add_i32 s49, s43, 0xa000
	global_load_lds_dwordx4 v[4:5], off
	v_lshl_add_u64 v[0:1], v[0:1], 0, s[16:17]
	s_mov_b32 m0, s48
	s_add_u32 s4, s34, 0x40080
	global_load_lds_dwordx4 v[0:1], off
	v_lshl_add_u64 v[0:1], v[2:3], 0, s[16:17]
	s_mov_b32 m0, s49
	s_addc_u32 s5, s35, 0
	global_load_lds_dwordx4 v[0:1], off
	s_add_i32 m0, s43, 0x1c000
	v_lshl_add_u64 v[0:1], s[4:5], 0, v[146:147]
	global_load_lds_dwordx4 v[0:1], off
	v_lshl_add_u64 v[0:1], s[4:5], 0, v[150:151]
	s_add_i32 m0, s43, 0x1e000
	s_cmpk_lt_u32 s18, 0x100
	global_load_lds_dwordx4 v[0:1], off
	s_waitcnt vmcnt(8)
	s_barrier
	v_bfe_u32 v1, v8, 4, 2
	v_and_b32_e32 v0, 15, v8
	v_lshlrev_b32_e32 v3, 4, v1
	v_lshl_or_b32 v153, s3, 6, v0
	v_lshl_or_b32 v0, v0, 6, v3
	v_lshlrev_b32_e32 v3, 2, v8
	v_and_b32_e32 v3, 32, v3
	v_bitop3_b32 v172, v0, s19, v3 bitop3:0xde
	s_cselect_b64 s[18:19], -1, 0
	s_ashr_i32 s50, s84, 31
	s_waitcnt lgkmcnt(0)
	s_ashr_i32 s54, s33, 31
	s_lshl_b32 s4, s47, 7
	s_add_u32 s4, s52, s4
	v_lshlrev_b32_e32 v2, 3, v1
	v_bitop3_b32 v4, v0, s2, v3 bitop3:0xde
	v_cmp_eq_u32_e64 s[2:3], 0, v1
	s_addc_u32 s5, s53, 0
	v_lshlrev_b32_e32 v0, 5, v1
	v_mov_b32_e32 v1, v147
	v_lshl_add_u64 v[154:155], s[4:5], 0, v[0:1]
	v_lshlrev_b32_e32 v0, 14, v9
	v_and_b32_e32 v0, 0xffff8000, v0
	v_lshl_add_u32 v0, v10, 11, v0
	v_and_b32_e32 v1, 1, v9
	v_lshl_or_b32 v0, v1, 6, v0
	v_lshl_add_u32 v156, v11, 1, v0
	v_lshlrev_b32_e32 v0, 14, v12
	v_and_b32_e32 v0, 0xffff8000, v0
	v_lshl_add_u32 v0, v13, 11, v0
	v_and_b32_e32 v1, 1, v12
	s_waitcnt vmcnt(6)
	v_lshl_or_b32 v0, v1, 6, v0
	v_lshl_add_u32 v158, v14, 1, v0
	s_add_i32 s55, 0, 0x10000
	s_add_i32 s56, 0, 0x14000
	v_mbcnt_lo_u32_b32 v0, -1, 0
	v_lshl_or_b32 v152, s47, 5, v2
	s_mov_b32 s51, s84
	v_mov_b32_e32 v157, v147
	v_mov_b32_e32 v159, v147
	v_mov_b64_e32 v[160:161], 0x100
	v_mov_b64_e32 v[162:163], 0xff
	v_add_u32_e32 v173, s55, v172
	v_add_u32_e32 v174, s56, v172
	v_add_u32_e32 v175, 0, v4
	v_mbcnt_hi_u32_b32 v176, -1, v0
	s_mov_b32 s57, 0
	s_barrier
	s_branch .LBB0_875

; #define PG8_STAGE(bufoff, gbase, voff) do { _Pragma("unroll") for (int _i = 0; _i < 2; ++_i) \
;         __builtin_amdgcn_global_load_lds((const unsigned*)((const char*)(gbase) + (voff)[_i]), (PG8_LAS unsigned*)(lds + (bufoff) + ldsw + _i * 8192), 16, 0, 0); } while (0)
; #define PG8_WAIT_V(n) asm volatile("s_waitcnt vmcnt(" #n ")" ::: "memory")
; #define PG8_BAR __builtin_amdgcn_s_barrier()
; template <class Epi, class Sched, bool ALIGN_EPI = false, bool SP2 = false>
; __device__ __forceinline__ void gemm_phase(PG8_LAS unsigned char* lds, const Gemm g, const Sched& S, const Epi& E) {
;     ...
;     const char* cA = (const char*)g.A + (size_t)cur.pm * tstep + cur.kh * khb; const char* cB = (const char*)g.Bt + (size_t)cur.pn * tstep + cur.kh * khb;
;     S.a_ready(cur);
;     if constexpr (SP2) {
;         PG8_STAGE(PG8_SB(0, 0), cB, voffB); PG8_STAGE(PG8_SB(0, 1), cB + hstep, voffB); PG8_STAGE(PG8_SA(0, 0), cA, voffA); PG8_STAGE(PG8_SA(0, 1), cA + hstep, voffA);
;         if (wr == 1) PG8_BAR;
;         PG8_WAIT_V(2); PG8_BAR;
;         PG8_STAGE(PG8_SB(1, 0), cB + kstep, voffB); PG8_STAGE(PG8_SA(1, 0), cA + kstep, voffA); PG8_STAGE(PG8_SB(1, 1), cB + hstep + kstep, voffB);
;         PG8_WAIT_V(6); PG8_BAR;
.LBB0_963:
	s_add_u32 s8, s72, 0x4b00000
	s_addc_u32 s9, s73, 0
	s_lshl_b32 s10, s10, 5
	s_and_b32 s15, s10, 0x60
	s_mov_b64 s[10:11], 0x80
	s_add_i32 m0, s39, 0x18000
	v_lshl_add_u64 v[6:7], v[6:7], 0, s[10:11]
	s_lshl_b32 s14, s4, 13
	s_lshl_b32 s16, s15, 7
	global_load_lds_dwordx4 v[6:7], off
	v_lshl_add_u64 v[4:5], v[4:5], 0, s[10:11]
	s_add_i32 m0, s39, 0x1a000
	s_add_i32 s43, s39, 0x8000
	s_add_i32 s44, s39, 0xa000
	global_load_lds_dwordx4 v[4:5], off
	v_lshl_add_u64 v[0:1], v[0:1], 0, s[10:11]
	s_mov_b32 m0, s43
	s_add_u32 s12, s26, 0x40080
	global_load_lds_dwordx4 v[0:1], off
	v_lshl_add_u64 v[0:1], v[2:3], 0, s[10:11]
	s_mov_b32 m0, s44
	s_addc_u32 s13, s27, 0
	global_load_lds_dwordx4 v[0:1], off
	s_add_i32 m0, s39, 0x1c000
	v_lshl_add_u64 v[0:1], s[12:13], 0, v[156:157]
	global_load_lds_dwordx4 v[0:1], off
	v_lshl_add_u64 v[0:1], s[12:13], 0, v[152:153]
	s_add_i32 m0, s39, 0x1e000
	v_bfe_u32 v2, v10, 4, 2
	global_load_lds_dwordx4 v[0:1], off
	s_waitcnt vmcnt(8)
	s_barrier
	v_and_b32_e32 v1, 15, v10
	v_lshlrev_b32_e32 v0, 3, v2
	v_lshlrev_b32_e32 v160, 4, v2
	v_lshlrev_b32_e32 v2, 2, v10
	v_lshl_or_b32 v189, s4, 6, v1
	v_lshl_or_b32 v1, v1, 6, v160
	v_and_b32_e32 v2, 32, v2
	v_bitop3_b32 v4, v1, s14, v2 bitop3:0xde
	v_bitop3_b32 v190, v1, s16, v2 bitop3:0xde
	v_lshlrev_b32_e32 v1, 14, v13
	s_sext_i32_i16 s23, s2
	s_cmpk_lt_u32 s3, 0x100
	v_lshl_add_u64 v[2:3], s[72:73], 0, v[160:161]
	s_mov_b64 s[2:3], 0x100000
	v_and_b32_e32 v1, 0xffff8000, v1
	v_lshl_add_u64 v[162:163], v[2:3], 0, s[2:3]
	v_lshl_add_u32 v1, v12, 11, v1
	v_and_b32_e32 v2, 1, v13
	v_lshl_or_b32 v1, v2, 6, v1
	v_lshl_add_u32 v164, v14, 1, v1
	v_lshlrev_b32_e32 v1, 14, v8
	v_and_b32_e32 v1, 0xffff8000, v1
	v_lshl_add_u32 v1, v9, 11, v1
	v_and_b32_e32 v2, 1, v8
	s_waitcnt vmcnt(6)
	v_lshl_or_b32 v1, v2, 6, v1
	s_cselect_b64 s[12:13], -1, 0
	v_lshl_add_u32 v166, v11, 1, v1
	s_add_i32 s47, 0, 0x10000
	s_add_i32 s48, 0, 0x14000
	v_mbcnt_lo_u32_b32 v1, -1, 0
	s_ashr_i32 s45, s84, 31
	s_mov_b32 s46, s84
	v_mov_b32_e32 v165, v161
	v_mov_b32_e32 v167, v161
	v_mov_b64_e32 v[168:169], 0x580
	v_mov_b64_e32 v[170:171], 0x57f
	v_add_u32_e32 v191, s47, v190
	v_add_u32_e32 v192, s48, v190
	v_add_u32_e32 v193, 0, v4
	v_mbcnt_hi_u32_b32 v194, -1, v1
	v_mov_b32_e32 v195, 0x358637bd
	s_movk_i32 s49, 0x1600
	s_lshl_b32 s4, s15, 1
	v_lshlrev_b32_e32 v160, 1, v0
	s_mov_b32 s100, -1
	s_mov_b32 s50, s5
	s_barrier
	s_branch .LBB0_966

; #define PG8_STAGE(bufoff, gbase, voff) do { _Pragma("unroll") for (int _i = 0; _i < 2; ++_i) \
;         __builtin_amdgcn_global_load_lds((const unsigned*)((const char*)(gbase) + (voff)[_i]), (PG8_LAS unsigned*)(lds + (bufoff) + ldsw + _i * 8192), 16, 0, 0); } while (0)
; #define PG8_WAIT_V(n) asm volatile("s_waitcnt vmcnt(" #n ")" ::: "memory")
; #define PG8_BAR __builtin_amdgcn_s_barrier()
; template <class Epi, class Sched, bool ALIGN_EPI = false, bool SP2 = false>
; __device__ __forceinline__ void gemm_phase(PG8_LAS unsigned char* lds, const Gemm g, const Sched& S, const Epi& E) {
;     ...
;     const char* cA = (const char*)g.A + (size_t)cur.pm * tstep + cur.kh * khb; const char* cB = (const char*)g.Bt + (size_t)cur.pn * tstep + cur.kh * khb;
;     S.a_ready(cur);
;     if constexpr (SP2) {
;         PG8_STAGE(PG8_SB(0, 0), cB, voffB); PG8_STAGE(PG8_SB(0, 1), cB + hstep, voffB); PG8_STAGE(PG8_SA(0, 0), cA, voffA); PG8_STAGE(PG8_SA(0, 1), cA + hstep, voffA);
;         if (wr == 1) PG8_BAR;
;         PG8_WAIT_V(2); PG8_BAR;
;         PG8_STAGE(PG8_SB(1, 0), cB + kstep, voffB); PG8_STAGE(PG8_SA(1, 0), cA + kstep, voffA); PG8_STAGE(PG8_SB(1, 1), cB + hstep + kstep, voffB);
;         PG8_WAIT_V(6); PG8_BAR;
.LBB0_1038:
	s_add_u32 s6, s72, 0xdb00000
	s_addc_u32 s7, s73, 0
	s_lshl_b32 s8, s8, 5
	s_and_b32 s14, s8, 0x60
	s_mov_b64 s[8:9], 0x80
	s_add_i32 m0, s38, 0x18000
	v_lshl_add_u64 v[6:7], v[6:7], 0, s[8:9]
	s_lshl_b32 s12, s0, 13
	s_lshl_b32 s13, s14, 7
	global_load_lds_dwordx4 v[6:7], off
	v_lshl_add_u64 v[4:5], v[4:5], 0, s[8:9]
	s_add_i32 m0, s38, 0x1a000
	s_add_i32 s43, s38, 0x8000
	s_add_i32 s44, s38, 0xa000
	global_load_lds_dwordx4 v[4:5], off
	v_lshl_add_u64 v[0:1], v[0:1], 0, s[8:9]
	s_mov_b32 m0, s43
	s_add_u32 s10, s24, 0xb0080
	global_load_lds_dwordx4 v[0:1], off
	v_lshl_add_u64 v[0:1], v[2:3], 0, s[8:9]
	s_mov_b32 m0, s44
	s_addc_u32 s11, s25, 0
	global_load_lds_dwordx4 v[0:1], off
	s_add_i32 m0, s38, 0x1c000
	v_lshl_add_u64 v[0:1], s[10:11], 0, v[130:131]
	global_load_lds_dwordx4 v[0:1], off
	v_lshl_add_u64 v[0:1], s[10:11], 0, v[134:135]
	s_add_i32 m0, s38, 0x1e000
	s_sext_i32_i8 s51, s3
	global_load_lds_dwordx4 v[0:1], off
	s_waitcnt vmcnt(8)
	s_barrier
	v_lshrrev_b32_e32 v1, 1, v188
	v_and_b32_e32 v1, 24, v1
	v_and_b32_e32 v0, 15, v188
	v_lshlrev_b32_e32 v2, 1, v1
	v_lshl_or_b32 v137, s0, 6, v0
	v_lshl_or_b32 v0, v0, 6, v2
	v_lshlrev_b32_e32 v2, 2, v188
	v_and_b32_e32 v2, 32, v2
	v_bitop3_b32 v3, v0, s12, v2 bitop3:0xde
	v_bitop3_b32 v152, v0, s13, v2 bitop3:0xde
	v_or_b32_e32 v136, s14, v1
	v_lshrrev_b32_e32 v1, 1, v8
	v_mul_lo_u32 v0, v10, s1
	s_mov_b32 s0, 0xb000
	s_cmpk_lt_u32 s2, 0x100
	v_mad_u64_u32 v[0:1], s[2:3], v1, s0, v[0:1]
	v_or_b32_e32 v0, v0, v9
	s_mov_b64 s[12:13], 0xb0080
	v_add_lshl_u32 v0, v0, v11, 1
	v_mov_b32_e32 v1, v131
	v_lshl_add_u64 v[138:139], v[0:1], 0, s[12:13]
	v_lshrrev_b32_e32 v1, 1, v12
	v_mul_lo_u32 v0, v13, s1
	v_mad_u64_u32 v[0:1], s[0:1], v1, s0, v[0:1]
	s_waitcnt vmcnt(6)
	v_or_b32_e32 v0, v0, v14
	s_cselect_b64 s[10:11], -1, 0
	v_add_lshl_u32 v0, v0, v15, 1
	v_mov_b32_e32 v1, v131
	s_add_i32 s46, 0, 0x10000
	s_add_i32 s47, 0, 0x14000
	s_ashr_i32 s45, s84, 31
	v_lshl_add_u64 v[140:141], v[0:1], 0, s[12:13]
	v_mov_b64_e32 v[142:143], 0x100
	v_mov_b64_e32 v[144:145], 0xff
	v_add_u32_e32 v153, s46, v152
	v_add_u32_e32 v154, s47, v152
	v_add_u32_e32 v155, 0, v3
	s_mov_b64 s[12:13], 0x20000
	s_mov_b64 s[14:15], 0x24000
	s_mov_b64 s[16:17], 0x28000
	s_mov_b64 s[18:19], 0x2c000
	s_barrier
	s_branch .LBB0_1041
